# chunkB: zc/zg rows of the next chunk loaded row-contiguously and staged through LDS
# speedup vs baseline: 1.0052x; 1.0052x over previous
; __global__ void __launch_bounds__(512, 2) hymba_fwd(Args A) {
;     ...
;         for (;;) {
;             if (tid == 0) *s_item = (int)atomicAdd(ctl + CW_WORK + 1, 1u);
;             __syncthreads();
;             const int it = *s_item;
;             __syncthreads();
;             if (it >= N_PB) break;
;             chunkB_item(A, lds, tid, lane, wave, it);
.LBB0_275:
	s_or_b64 exec, exec, s[12:13]
	v_mov_b32_e32 v0, s34
	s_waitcnt lgkmcnt(0)
	s_barrier
	ds_read_b32 v0, v0
	s_movk_i32 s13, 0x7f
	s_mov_b64 s[14:15], -1
	s_waitcnt lgkmcnt(0)
	s_barrier
	v_cmp_lt_i32_e32 vcc, s13, v0
	v_readfirstlane_b32 s12, v0
	s_cbranch_vccnz .LBB0_270
	s_mov_b32 s100, 0x10001
	s_mov_b32 s101, 0x10001
	s_lshr_b32 s98, s12, 3
	s_mul_i32 s98, s98, 0xe00000
	s_add_u32 s98, s94, s98
	s_addc_u32 s99, s95, 0
	v_lshrrev_b32_e32 v240, 4, v144
	v_lshrrev_b32_e32 v241, 6, v144
	v_lshl_add_u32 v240, v241, 2, v240
	v_and_b32_e32 v241, 15, v144
	v_mul_u32_u24_e32 v242, 0x90, v240
	v_lshl_add_u32 v242, v241, 3, v242
	v_add_u32_e32 v242, 0x6000, v242
	v_mul_u32_u24_e32 v240, 0x1c00, v240
	v_lshl_add_u32 v240, v241, 3, v240
	s_and_b32 s22, s12, 7
	s_lshl_b32 s22, s22, 7
	s_add_i32 s22, s22, 0x800
	v_add_u32_e32 v240, s22, v240
	v_add_u32_e32 v241, 0x7000, v240
	v_mul_u32_u24_e32 v243, 0x90, v96
	v_lshl_add_u32 v243, v92, 1, v243
	v_add_u32_e32 v243, 0x6000, v243
	global_load_dwordx2 v[182:183], v240, s[98:99]
	global_load_dwordx2 v[188:189], v241, s[98:99]
	global_load_dwordx2 v[184:185], v240, s[98:99] offset:1280
	global_load_dwordx2 v[190:191], v241, s[98:99] offset:1280
	s_and_b32 s38, s12, 7
	s_ashr_i32 s13, s12, 31
	s_mul_i32 s14, s12, 0xc0000
	s_mul_hi_i32 s15, s12, 0xc0000
	s_add_u32 s14, s86, s14
	s_addc_u32 s15, s87, s15
	s_add_u32 s16, s14, 0x2000
	v_lshlrev_b32_e32 v94, 8, v91
	v_lshl_add_u32 v94, v132, 4, v94
	s_addc_u32 s17, s15, 0
	v_lshl_add_u64 v[8:9], s[14:15], 0, v[94:95]
	v_mov_b32_e32 v125, v95
	v_mov_b32_e32 v127, v95
	v_lshl_add_u64 v[4:5], v[8:9], 0, v[124:125]
	v_lshl_add_u64 v[10:11], v[98:99], 2, s[16:17]
	v_lshl_add_u64 v[12:13], v[100:101], 2, s[16:17]
	v_lshl_add_u64 v[14:15], v[102:103], 2, s[16:17]
	v_lshl_add_u64 v[8:9], v[8:9], 0, v[126:127]
	global_load_dwordx4 v[0:3], v[4:5], off
	s_nop 0
	global_load_dwordx4 v[4:7], v[4:5], off offset:1024
	v_lshl_add_u64 v[16:17], v[104:105], 2, s[16:17]
	global_load_dword v210, v[10:11], off
	global_load_dword v211, v[12:13], off
	global_load_dword v212, v[14:15], off
	global_load_dword v213, v[16:17], off
	global_load_dwordx4 v[36:39], v[8:9], off
	global_load_dwordx4 v[20:23], v[8:9], off offset:1024
	v_lshl_add_u64 v[8:9], v[108:109], 2, s[16:17]
	v_lshl_add_u64 v[10:11], v[110:111], 2, s[16:17]
	v_lshl_add_u64 v[12:13], v[112:113], 2, s[16:17]
	v_lshl_add_u64 v[14:15], v[114:115], 2, s[16:17]
	s_ashr_i32 s14, s12, 3
	s_lshl_b64 s[16:17], s[12:13], 19
	s_add_u32 s18, s3, s16
	s_addc_u32 s19, s11, s17
	v_mov_b32_e32 v149, v95
	global_load_dword v40, v[8:9], off
	global_load_dword v41, v[10:11], off
	global_load_dword v42, v[12:13], off
	global_load_dword v43, v[14:15], off
	v_lshl_add_u64 v[8:9], s[18:19], 0, v[148:149]
	s_ashr_i32 s15, s14, 31
	v_lshl_add_u64 v[16:17], s[18:19], 0, v[94:95]
	v_lshl_add_u64 v[18:19], v[8:9], 0, s[8:9]
	s_lshl_b64 s[16:17], s[14:15], 11
	v_lshl_add_u64 v[12:13], v[16:17], 0, v[124:125]
	v_lshl_add_u64 v[24:25], v[18:19], 0, v[124:125]
	global_load_dwordx4 v[8:11], v[12:13], off
	s_nop 0
	global_load_dwordx4 v[12:15], v[12:13], off offset:1024
	v_or_b32_e32 v27, s16, v96
	global_load_dwordx2 v[196:197], v[24:25], off
	v_mov_b64_e32 v[24:25], s[94:95]
	v_lshl_add_u32 v26, s38, 6, v92
	v_mad_u64_u32 v[24:25], s[18:19], v27, s35, v[24:25]
	v_mad_i32_i24 v25, s17, v147, v25
	v_lshlrev_b32_e32 v150, 1, v26
	v_mov_b32_e32 v151, v95
	v_lshl_add_u64 v[24:25], v[24:25], 0, v[150:151]
	global_load_dwordx2 v[174:175], v[24:25], off offset:2048
	v_mov_b32_e32 v170, v95
	v_mov_b32_e32 v171, v95
	s_and_saveexec_b64 s[18:19], s[4:5]
	s_cbranch_execz .LBB0_278
	v_add_co_u32_e32 v28, vcc, 0xfffff000, v24
	s_nop 1
	v_addc_co_u32_e32 v29, vcc, -1, v25, vcc
	global_load_dwordx2 v[170:171], v[28:29], off offset:-1024

; __device__ __forceinline__ void chunkB_item(const Args& A, LAS unsigned char* lds, int tid, int lane, int wave, int bh) {
;     ...
;         for (int nn = 0; nn < 2; ++nn) { p0[nn][0] = p1[nn][0]; p0[nn][1] = p1[nn][1]; q0[nn] = q1[nn]; r0_[nn][0] = r1_[nn][0]; r0_[nn][1] = r1_[nn][1];
;             ya0[nn] = ya1[nn]; zc0[nn] = zc1[nn]; zp0[nn] = zp1[nn]; zg0[nn] = zg1[nn]; bc0[nn] = bc1[nn]; }
.LBB0_279:
	s_or_b64 exec, exec, s[22:23]
	s_waitcnt lgkmcnt(0)
	s_barrier
	v_mov_b32_dpp v170, v174 row_shr:1 row_mask:0xf bank_mask:0xf
	v_mov_b32_dpp v171, v175 row_shr:1 row_mask:0xf bank_mask:0xf
	v_mov_b32_dpp v164, v174 row_ror:1 row_mask:0xf bank_mask:0xf
	v_mov_b32_dpp v165, v175 row_ror:1 row_mask:0xf bank_mask:0xf
	v_mov_b32_dpp v164, v168 row_shr:1 row_mask:0xf bank_mask:0xf
	v_mov_b32_dpp v165, v169 row_shr:1 row_mask:0xf bank_mask:0xf
	ds_read2st64_b64 v[20:23], v141 offset0:36 offset1:37
	s_waitcnt lgkmcnt(1)
	ds_read2st64_b64 v[36:39], v141 offset0:38 offset1:39
	v_lshlrev_b32_e32 v42, 16, v176
	v_and_b32_e32 v43, 0xffff0000, v176
	v_lshlrev_b32_e32 v40, 16, v174
	s_waitcnt lgkmcnt(1)
	v_pk_add_f32 v[20:21], v[20:21], 0 op_sel_hi:[1,0]
	v_and_b32_e32 v41, 0xffff0000, v174
	v_pk_add_f32 v[20:21], v[20:21], v[22:23]
	v_mul_f32_e32 v23, 0xbfb8aa3b, v42
	s_waitcnt lgkmcnt(0)
	v_pk_add_f32 v[20:21], v[20:21], v[36:37]
	v_exp_f32_e32 v23, v23
	v_pk_add_f32 v[20:21], v[20:21], v[38:39]
	v_lshlrev_b32_e32 v36, 16, v170
	v_pk_mul_f32 v[20:21], v[20:21], s[10:11] op_sel_hi:[1,0]
	v_add_f32_e32 v23, 1.0, v23
	v_fma_f32 v22, -v20, v20, v21
	v_max_f32_e32 v22, 0, v22
	v_add_f32_e32 v22, 0x3a27c5ac, v22
	v_rcp_f32_e32 v38, v23
	v_mul_f32_e32 v23, 0xbfb8aa3b, v43
	v_rsq_f32_e32 v22, v22
	v_exp_f32_e32 v23, v23
	v_and_b32_e32 v37, 0xffff0000, v170
	v_pk_add_f32 v[56:57], v[198:199], v[20:21] op_sel_hi:[1,0] neg_lo:[0,1] neg_hi:[0,1]
	v_pk_add_f32 v[36:37], v[36:37], v[40:41] neg_lo:[0,1] neg_hi:[0,1]
	v_pk_mul_f32 v[56:57], v[56:57], v[22:23] op_sel_hi:[1,0]
	v_add_f32_e32 v23, 1.0, v23
	s_waitcnt vmcnt(0)
	v_pk_fma_f32 v[36:37], v[36:37], v[60:61], v[40:41]
	v_lshlrev_b32_e32 v40, 16, v177
	v_rcp_f32_e32 v39, v23
	v_mul_f32_e32 v23, 0xbfb8aa3b, v40
	v_exp_f32_e32 v23, v23
	v_pk_fma_f32 v[56:57], v[64:65], v[56:57], v[68:69]
	v_and_b32_e32 v41, 0xffff0000, v177
	v_pk_fma_f32 v[36:37], v[172:173], v[36:37], v[56:57] op_sel_hi:[0,1,1]
	v_add_f32_e32 v23, 1.0, v23
	v_rcp_f32_e32 v56, v23
	v_mul_f32_e32 v23, 0xbfb8aa3b, v41
	v_exp_f32_e32 v23, v23
	v_pk_add_f32 v[20:21], v[196:197], v[20:21] op_sel_hi:[1,0] neg_lo:[0,1] neg_hi:[0,1]
	v_pk_mul_f32 v[38:39], v[38:39], v[42:43]
	v_lshlrev_b32_e32 v42, 16, v171
	v_pk_mul_f32 v[20:21], v[20:21], v[22:23] op_sel_hi:[1,0]
	v_add_f32_e32 v22, 1.0, v23
	v_rcp_f32_e32 v57, v22
	v_pk_mul_f32 v[36:37], v[38:39], v[36:37]
	v_lshlrev_b32_e32 v38, 16, v175
	v_and_b32_e32 v39, 0xffff0000, v175
	v_and_b32_e32 v43, 0xffff0000, v171
	v_pk_add_f32 v[22:23], v[42:43], v[38:39] neg_lo:[0,1] neg_hi:[0,1]
	v_pk_fma_f32 v[20:21], v[66:67], v[20:21], v[70:71]
	v_pk_fma_f32 v[22:23], v[22:23], v[62:63], v[38:39]
	v_lshl_add_u64 v[42:43], v[160:161], 0, s[20:21]
	v_pk_fma_f32 v[20:21], v[172:173], v[22:23], v[20:21] op_sel_hi:[0,1,1]
	v_pk_mul_f32 v[22:23], v[56:57], v[40:41]
	v_cvt_pk_bf16_f32 v40, v36, v37
	v_pk_mul_f32 v[38:39], v[22:23], v[20:21]
	ds_read2st64_b64 v[20:23], v143 offset0:36 offset1:37
	v_cvt_pk_bf16_f32 v41, v38, v39
	ds_read2st64_b64 v[36:39], v143 offset0:38 offset1:39
	global_store_dwordx2 v[42:43], v[40:41], off
	v_lshlrev_b32_e32 v40, 16, v164
	s_waitcnt lgkmcnt(1)
	v_pk_add_f32 v[20:21], v[20:21], 0 op_sel_hi:[1,0]
	v_and_b32_e32 v41, 0xffff0000, v164
	v_pk_add_f32 v[20:21], v[20:21], v[22:23]
	v_mov_b64_e32 v[58:59], v[46:47]
	s_waitcnt lgkmcnt(0)
	v_pk_add_f32 v[20:21], v[20:21], v[36:37]
	v_lshlrev_b32_e32 v36, 16, v168
	v_pk_add_f32 v[20:21], v[20:21], v[38:39]
	v_lshlrev_b32_e32 v38, 16, v166
	v_mul_f32_e32 v23, 0xbfb8aa3b, v38
	v_exp_f32_e32 v23, v23
	v_pk_mul_f32 v[20:21], v[20:21], s[10:11] op_sel_hi:[1,0]
	v_and_b32_e32 v39, 0xffff0000, v166
	v_fma_f32 v22, -v20, v20, v21
	v_max_f32_e32 v22, 0, v22
	v_add_f32_e32 v23, 1.0, v23
	v_add_f32_e32 v22, 0x3a27c5ac, v22
	v_rcp_f32_e32 v42, v23
	v_mul_f32_e32 v23, 0xbfb8aa3b, v39
	v_rsq_f32_e32 v22, v22
	v_exp_f32_e32 v23, v23
	v_and_b32_e32 v37, 0xffff0000, v168
	v_pk_add_f32 v[54:55], v[54:55], v[20:21] op_sel_hi:[1,0] neg_lo:[0,1] neg_hi:[0,1]
	v_pk_add_f32 v[40:41], v[40:41], v[36:37] neg_lo:[0,1] neg_hi:[0,1]
	v_pk_mul_f32 v[54:55], v[54:55], v[22:23] op_sel_hi:[1,0]
	v_add_f32_e32 v23, 1.0, v23
	v_pk_fma_f32 v[36:37], v[40:41], v[60:61], v[36:37]
	v_lshlrev_b32_e32 v40, 16, v167
	v_rcp_f32_e32 v43, v23
	v_mul_f32_e32 v23, 0xbfb8aa3b, v40
	v_exp_f32_e32 v23, v23
	v_pk_fma_f32 v[54:55], v[64:65], v[54:55], v[68:69]
	v_and_b32_e32 v41, 0xffff0000, v167
	v_pk_fma_f32 v[36:37], v[162:163], v[36:37], v[54:55] op_sel_hi:[0,1,1]
	v_add_f32_e32 v23, 1.0, v23
	v_rcp_f32_e32 v54, v23
	v_mul_f32_e32 v23, 0xbfb8aa3b, v41
	v_exp_f32_e32 v23, v23
	v_pk_add_f32 v[20:21], v[52:53], v[20:21] op_sel_hi:[1,0] neg_lo:[0,1] neg_hi:[0,1]
	v_pk_mul_f32 v[38:39], v[42:43], v[38:39]
	v_lshlrev_b32_e32 v42, 16, v165
	v_pk_mul_f32 v[20:21], v[20:21], v[22:23] op_sel_hi:[1,0]
	v_add_f32_e32 v22, 1.0, v23
	v_rcp_f32_e32 v55, v22
	v_pk_mul_f32 v[36:37], v[38:39], v[36:37]
	v_lshlrev_b32_e32 v38, 16, v169
	v_and_b32_e32 v39, 0xffff0000, v169
	v_and_b32_e32 v43, 0xffff0000, v165
	v_pk_add_f32 v[22:23], v[42:43], v[38:39] neg_lo:[0,1] neg_hi:[0,1]
	v_pk_fma_f32 v[20:21], v[66:67], v[20:21], v[70:71]
	v_pk_fma_f32 v[22:23], v[22:23], v[62:63], v[38:39]
	v_mov_b64_e32 v[164:165], v[192:193]
	v_pk_fma_f32 v[20:21], v[162:163], v[22:23], v[20:21] op_sel_hi:[0,1,1]
	v_pk_mul_f32 v[22:23], v[54:55], v[40:41]
	v_mov_b64_e32 v[54:55], v[50:51]
	v_pk_mul_f32 v[20:21], v[22:23], v[20:21]
	v_cvt_pk_bf16_f32 v22, v36, v37
	v_cvt_pk_bf16_f32 v23, v20, v21
	v_lshl_add_u64 v[20:21], v[158:159], 0, s[20:21]
	s_add_u32 s20, s20, 0x20000
	global_store_dwordx2 v[20:21], v[22:23], off
	s_addc_u32 s21, s21, 0
	s_add_i32 s39, s39, 1
	v_mov_b64_e32 v[38:39], v[26:27]
	v_mov_b64_e32 v[20:21], v[28:29]
	s_cmp_eq_u32 s20, 0x400000
	v_mov_b64_e32 v[170:171], v[186:187]
	v_mov_b64_e32 v[166:167], v[190:191]
	v_mov_b64_e32 v[176:177], v[184:185]
	v_mov_b64_e32 v[174:175], v[182:183]
	v_mov_b64_e32 v[168:169], v[188:189]
	v_mov_b32_e32 v162, v127
	v_mov_b32_e32 v172, v125
	v_mov_b64_e32 v[56:57], v[44:45]
	v_mov_b64_e32 v[52:53], v[48:49]
	v_mov_b64_e32 v[36:37], v[24:25]
	v_mov_b64_e32 v[22:23], v[30:31]
	v_mov_b32_e32 v40, v216
	v_mov_b32_e32 v41, v217
	v_mov_b32_e32 v42, v218
	v_mov_b32_e32 v43, v219
	v_mov_b32_e32 v196, v178
	v_mov_b32_e32 v197, v179
	v_mov_b32_e32 v194, v180
	v_mov_b32_e32 v195, v181
	s_cbranch_scc1 .LBB0_268
.LBB0_280:
	s_cmp_lg_u32 s20, 0x3e0000
	s_cselect_b32 s15, s39, 31
	s_add_u32 s22, s18, s15
	s_addc_u32 s23, s19, 0
	s_mul_i32 s40, s23, 0x6000
	s_mul_hi_u32 s41, s22, 0x6000
	s_add_i32 s41, s41, s40
	s_mul_i32 s40, s22, 0x6000
	s_add_u32 s40, s86, s40
	s_addc_u32 s41, s87, s41
	s_waitcnt vmcnt(12)
	ds_write_b64 v242, v[182:183]
	ds_write_b64 v242, v[188:189] offset:576
	ds_write_b64 v242, v[184:185] offset:9216
	ds_write_b64 v242, v[190:191] offset:9792
	v_mov_b64_e32 v[226:227], v[10:11]
	s_add_u32 s42, s40, 0x2000
	v_mov_b64_e32 v[224:225], v[8:9]
	s_addc_u32 s43, s41, 0
	v_lshl_add_u64 v[8:9], s[40:41], 0, v[94:95]
	s_lshl_b64 s[40:41], s[22:23], 14
	s_add_u32 s40, s3, s40
	s_addc_u32 s41, s11, s41
	s_lshl_b64 s[22:23], s[22:23], 8
	s_add_u32 s22, s24, s22
	v_mov_b64_e32 v[74:75], v[6:7]
	v_mov_b32_e32 v125, v95
	v_mov_b32_e32 v127, v95
	s_addc_u32 s23, s25, s23
	s_lshl_b32 s15, s15, 6
	v_mov_b64_e32 v[72:73], v[4:5]
	v_mov_b64_e32 v[200:201], v[2:3]
	s_waitcnt vmcnt(11)
	v_mov_b64_e32 v[222:223], v[14:15]
	v_lshl_add_u64 v[4:5], v[8:9], 0, v[124:125]
	v_lshl_add_u64 v[10:11], v[98:99], 2, s[42:43]
	v_lshl_add_u64 v[24:25], v[104:105], 2, s[42:43]
	v_lshl_add_u64 v[8:9], v[8:9], 0, v[126:127]
	s_add_u32 s15, s16, s15
	v_mov_b64_e32 v[198:199], v[0:1]
	v_mov_b64_e32 v[220:221], v[12:13]
	v_mov_b32_e32 v76, v210
	v_mov_b32_e32 v77, v211
	v_mov_b32_e32 v78, v212
	v_mov_b32_e32 v79, v213
	global_load_dwordx4 v[0:3], v[4:5], off
	s_nop 0
	global_load_dwordx4 v[4:7], v[4:5], off offset:1024
	v_lshl_add_u64 v[12:13], v[100:101], 2, s[42:43]
	v_lshl_add_u64 v[14:15], v[102:103], 2, s[42:43]
	global_load_dword v210, v[10:11], off
	global_load_dword v211, v[12:13], off
	global_load_dword v212, v[14:15], off
	global_load_dword v213, v[24:25], off
	s_nop 0
	global_load_dwordx4 v[24:27], v[8:9], off
	global_load_dwordx4 v[28:31], v[8:9], off offset:1024
	v_lshl_add_u64 v[8:9], v[108:109], 2, s[42:43]
	v_mov_b32_e32 v149, v95
	v_or_b32_e32 v48, s15, v96
	v_mov_b64_e32 v[62:63], s[94:95]
	v_lshl_add_u64 v[10:11], v[110:111], 2, s[42:43]
	v_lshl_add_u64 v[12:13], v[112:113], 2, s[42:43]
	v_lshl_add_u64 v[14:15], v[114:115], 2, s[42:43]
	global_load_dword v216, v[8:9], off
	global_load_dword v217, v[10:11], off
	global_load_dword v218, v[12:13], off
	global_load_dword v219, v[14:15], off
	s_addc_u32 s42, s17, 0
	v_lshl_add_u64 v[44:45], s[40:41], 0, v[94:95]
	v_lshl_add_u64 v[8:9], s[40:41], 0, v[148:149]
	v_mad_u64_u32 v[48:49], s[40:41], v48, s35, v[62:63]
	v_mad_i32_i24 v49, s42, v147, v49
	v_mov_b32_e32 v151, v95
	v_or_b32_e32 v64, s15, v106
	v_lshl_add_u64 v[48:49], v[48:49], 0, v[150:151]
	v_mad_u64_u32 v[62:63], s[40:41], v64, s35, v[62:63]
	v_add_co_u32_e32 v50, vcc, s36, v48
	v_mad_i32_i24 v63, s42, v147, v63
	v_lshl_add_u64 v[60:61], v[8:9], 0, s[8:9]
	v_addc_co_u32_e32 v51, vcc, -1, v49, vcc
	v_lshl_add_u64 v[62:63], v[62:63], 0, v[150:151]
	v_lshl_add_u64 v[12:13], v[44:45], 0, v[124:125]
	v_lshl_add_u64 v[46:47], v[60:61], 0, v[124:125]
	v_add_co_u32_e32 v64, vcc, s36, v62
	global_load_dwordx4 v[8:11], v[12:13], off
	s_nop 0
	global_load_dwordx4 v[12:15], v[12:13], off offset:1024
	s_nop 0
	global_load_dwordx2 v[178:179], v[46:47], off
	s_mul_i32 s98, s15, 0x1c00
	s_add_u32 s98, s98, s94
	s_addc_u32 s99, s95, 0
	global_load_dwordx2 v[182:183], v240, s[98:99]
	s_mov_b64 exec, s[100:101]
	global_load_dwordx2 v[186:187], v[50:51], off offset:-1024
	s_mov_b64 exec, -1
	global_load_dwordx2 v[184:185], v240, s[98:99] offset:1280
	v_lshl_add_u64 v[48:49], v[44:45], 0, v[126:127]
	v_lshl_add_u64 v[60:61], v[60:61], 0, v[126:127]
	v_addc_co_u32_e32 v65, vcc, -1, v63, vcc
	global_load_dwordx4 v[44:47], v[48:49], off
	s_nop 0
	global_load_dwordx4 v[48:51], v[48:49], off offset:1024
	s_nop 0
	global_load_dwordx2 v[180:181], v[60:61], off
	global_load_dwordx2 v[188:189], v241, s[98:99]
	s_mov_b64 exec, s[100:101]
	global_load_dwordx2 v[192:193], v[64:65], off offset:-1024
	s_mov_b64 exec, -1
	global_load_dwordx2 v[190:191], v241, s[98:99] offset:1280
	global_load_dword v125, v214, s[22:23]
	global_load_dword v127, v215, s[22:23]
	s_nop 0
	global_load_dwordx4 v[64:67], v[152:153], off
	global_load_dwordx4 v[68:71], v[154:155], off
	global_load_dwordx4 v[60:63], v[156:157], off
	v_cvt_pk_bf16_f32 v80, v16, 0
	v_lshlrev_b32_e32 v81, 16, v80
	v_sub_f32_e32 v16, v16, v81
	v_cvt_pk_bf16_f32 v16, v16, s0
	ds_write_b16 v107, v80
	ds_write_b16 v107, v16 offset:9216
	v_cvt_pk_bf16_f32 v16, v17, 0
	v_lshlrev_b32_e32 v80, 16, v16
	v_sub_f32_e32 v17, v17, v80
	v_cvt_pk_bf16_f32 v17, v17, s0
	ds_write_b16 v107, v16 offset:144
	ds_write_b16 v107, v17 offset:9360
	v_cvt_pk_bf16_f32 v16, v18, 0
	v_lshlrev_b32_e32 v17, 16, v16
	v_sub_f32_e32 v17, v18, v17
	v_cvt_pk_bf16_f32 v17, v17, s0
	ds_write_b16 v107, v16 offset:288
	ds_write_b16 v107, v17 offset:9504
	v_cvt_pk_bf16_f32 v16, v19, 0
	v_lshlrev_b32_e32 v17, 16, v16
	v_sub_f32_e32 v17, v19, v17
	v_cvt_pk_bf16_f32 v17, v17, s0
	ds_write_b16 v107, v16 offset:432
	ds_write_b16 v107, v17 offset:9648
	v_cvt_pk_bf16_f32 v16, v32, 0
	v_lshlrev_b32_e32 v17, 16, v16
	v_sub_f32_e32 v17, v32, v17
	v_cvt_pk_bf16_f32 v17, v17, s0
	ds_write_b16 v135, v16
	ds_write_b16 v135, v17 offset:9216
	v_cvt_pk_bf16_f32 v16, v33, 0
	v_lshlrev_b32_e32 v17, 16, v16
	v_sub_f32_e32 v17, v33, v17
	v_cvt_pk_bf16_f32 v17, v17, s0
	ds_write_b16 v135, v16 offset:144
	ds_write_b16 v135, v17 offset:9360
	v_cvt_pk_bf16_f32 v16, v34, 0
	v_lshlrev_b32_e32 v17, 16, v16
	v_sub_f32_e32 v17, v34, v17
	v_cvt_pk_bf16_f32 v17, v17, s0
	ds_write_b16 v135, v16 offset:288
	ds_write_b16 v135, v17 offset:9504
	v_cvt_pk_bf16_f32 v16, v35, 0
	v_lshlrev_b32_e32 v17, 16, v16
	v_sub_f32_e32 v17, v35, v17
	v_cvt_pk_bf16_f32 v17, v17, s0
	ds_write_b16 v135, v16 offset:432
	ds_write_b16 v135, v17 offset:9648
	s_waitcnt lgkmcnt(0)
	s_barrier
	ds_read_b128 v[80:83], v139
	ds_read_b128 v[32:35], v139 offset:64
	s_waitcnt lgkmcnt(1)
	v_mfma_f32_16x16x32_bf16 v[16:19], v[80:83], v[198:201], v[76:79]
	ds_read_b128 v[84:87], v139 offset:9216
	s_nop 1
	ds_read_b128 v[76:79], v139 offset:9280
	s_waitcnt vmcnt(39)
	v_lshlrev_b32_e32 v202, 16, v196
	v_and_b32_e32 v203, 0xffff0000, v196
	s_waitcnt lgkmcnt(1)
	v_mfma_f32_16x16x32_bf16 v[16:19], v[84:87], v[198:201], v[16:19]
	v_lshlrev_b32_e32 v196, 16, v197
	v_and_b32_e32 v197, 0xffff0000, v197
	v_and_b32_e32 v151, 64, v209
	v_mfma_f32_16x16x32_bf16 v[198:201], v[80:83], v[224:227], 0
	v_xor_b32_e32 v149, 16, v209
	v_add_u32_e32 v151, 64, v151
	v_cmp_lt_i32_e32 vcc, v149, v151
	v_mfma_f32_16x16x32_bf16 v[198:201], v[32:35], v[220:223], v[198:201]
	v_xor_b32_e32 v224, 32, v209
	v_cndmask_b32_e32 v149, v209, v149, vcc
	v_lshlrev_b32_e32 v149, 2, v149
	v_cmp_lt_i32_e32 vcc, v224, v151
	v_mfma_f32_16x16x32_bf16 v[16:19], v[32:35], v[72:75], v[16:19]
	s_nop 2
	v_add_f32_e64 v198, v198, v202
	v_add_f32_e64 v199, v199, v203
	v_pk_add_f32 v[196:197], v[200:201], v[196:197]
	v_pk_mul_f32 v[200:201], v[198:199], v[198:199]
	v_pk_mul_f32 v[202:203], v[196:197], v[196:197]
	v_mov_b32_e32 v220, v198
	v_mov_b32_e32 v221, v200
	v_mov_b32_e32 v200, v199
	v_pk_add_f32 v[200:201], v[220:221], v[200:201]
	v_mov_b32_e32 v220, v196
	v_mov_b32_e32 v221, v202
	v_mov_b32_e32 v202, v197
	v_pk_add_f32 v[202:203], v[220:221], v[202:203]
	v_cndmask_b32_e32 v151, v209, v224, vcc
	v_pk_add_f32 v[200:201], v[200:201], v[202:203]
	ds_bpermute_b32 v202, v149, v200
	ds_bpermute_b32 v203, v149, v201
	v_lshlrev_b32_e32 v151, 2, v151
	s_waitcnt lgkmcnt(2)
	v_mfma_f32_16x16x32_bf16 v[16:19], v[76:79], v[72:75], v[16:19]
	s_waitcnt lgkmcnt(0)
	v_pk_add_f32 v[200:201], v[200:201], v[202:203]
	ds_bpermute_b32 v202, v151, v200
	ds_bpermute_b32 v203, v151, v201
	s_and_saveexec_b64 s[22:23], s[30:31]
	s_cbranch_execz .LBB0_282
	s_waitcnt lgkmcnt(0)
	v_pk_add_f32 v[72:73], v[200:201], v[202:203]
	v_add_u32_e32 v74, s26, v130
	ds_write_b64 v74, v[72:73] offset:18432
.LBB0_282:
	s_or_b64 exec, exec, s[22:23]
	s_waitcnt vmcnt(35)
	v_mfma_f32_16x16x32_bf16 v[56:59], v[80:83], v[56:59], 0
	s_waitcnt vmcnt(33)
	v_lshlrev_b32_e32 v72, 16, v194
	v_and_b32_e32 v73, 0xffff0000, v194
	v_lshlrev_b32_e32 v74, 16, v195
	v_mfma_f32_16x16x32_bf16 v[54:57], v[32:35], v[52:55], v[56:59]
	v_and_b32_e32 v75, 0xffff0000, v195
	v_mfma_f32_16x16x32_bf16 v[40:43], v[80:83], v[36:39], v[40:43]
	v_mfma_f32_16x16x32_bf16 v[36:39], v[84:87], v[36:39], v[40:43]
	s_nop 4
	v_add_f32_e64 v54, v54, v72
	v_add_f32_e64 v55, v55, v73
	v_pk_add_f32 v[52:53], v[56:57], v[74:75]
	v_pk_mul_f32 v[56:57], v[54:55], v[54:55]
	v_pk_mul_f32 v[58:59], v[52:53], v[52:53]
	v_mov_b32_e32 v72, v54
	v_mov_b32_e32 v73, v56
	v_mov_b32_e32 v56, v55
	v_mov_b32_e32 v42, v52
	v_mov_b32_e32 v43, v58
	v_mov_b32_e32 v58, v53
	v_pk_add_f32 v[40:41], v[72:73], v[56:57]
	v_pk_add_f32 v[42:43], v[42:43], v[58:59]
	v_mfma_f32_16x16x32_bf16 v[32:35], v[32:35], v[20:23], v[36:39]
	v_add_f32_e64 v40, v40, v42
	v_add_f32_e64 v41, v41, v43
	ds_bpermute_b32 v42, v149, v40
	ds_bpermute_b32 v43, v149, v41
	v_mfma_f32_16x16x32_bf16 v[32:35], v[76:79], v[20:23], v[32:35]
	s_waitcnt lgkmcnt(0)
	v_pk_add_f32 v[36:37], v[40:41], v[42:43]
	ds_bpermute_b32 v38, v151, v36
	ds_bpermute_b32 v39, v151, v37
	ds_read_b64 v[174:175], v243
	ds_read_b64 v[168:169], v243 offset:2304
	ds_read_b64 v[176:177], v243 offset:9216
	ds_read_b64 v[166:167], v243 offset:11520
	s_and_saveexec_b64 s[22:23], s[30:31]
	s_cbranch_execz .LBB0_279
	s_waitcnt lgkmcnt(0)
	v_pk_add_f32 v[20:21], v[36:37], v[38:39]
	v_add_u32_e32 v22, s27, v130
	ds_write_b64 v22, v[20:21] offset:18432
	s_branch .LBB0_279
